# retention tile loop: LDS-DMA issue moved inside first QK MFMA batch; diagonal-factor copies only on diagonal path
# speedup vs baseline: 1.0067x; 1.0036x over previous
.LBB0_428:
	s_lshl_b32 s18, s15, 15
	s_add_i32 s20, s18, 0x18000
	s_and_b32 s20, s20, 0x18000
	s_add_i32 s20, s20, 0
	s_waitcnt vmcnt(8)
	s_barrier
	s_cmp_gt_i32 s19, s14
	s_cbranch_scc1 .Lret_skip_dma
	s_add_i32 s18, s18, 0
	v_add_u32_e32 v0, s18, v250
	v_add_u32_e32 v70, v0, v237
	v_add_u32_e32 v74, v0, v235
	ds_read_b128 v[66:69], v70
	ds_read_b128 v[70:73], v70 offset:8192
	ds_read_b128 v[188:191], v74
	ds_read_b128 v[202:205], v74 offset:8192
	v_add_u32_e32 v74, v0, v234
	ds_read_b128 v[206:209], v74
	ds_read_b128 v[210:213], v74 offset:8192
	v_add_u32_e32 v74, v0, v236
	ds_read_b128 v[214:217], v74
	ds_read_b128 v[218:221], v74 offset:8192
	s_mov_b32 s22, m0
	s_waitcnt lgkmcnt(7)
	v_mfma_f32_32x32x16_bf16 v[82:97], v[66:69], v[126:129], 0
	s_add_i32 s21, s29, s20
	s_mov_b32 m0, s21
	v_lshl_add_u64 v[226:227], v[186:187], 0, s[16:17]
	global_load_lds_dwordx4 v[226:227], off
	s_waitcnt lgkmcnt(6)
	v_mfma_f32_32x32x16_bf16 v[66:81], v[70:73], v[126:129], 0
	s_waitcnt lgkmcnt(5)
	v_mfma_f32_32x32x16_bf16 v[82:97], v[188:191], v[122:125], v[82:97]
	s_add_i32 s21, s30, s20
	s_mov_b32 m0, s21
	v_lshl_add_u64 v[226:227], v[184:185], 0, s[16:17]
	global_load_lds_dwordx4 v[226:227], off
	s_waitcnt lgkmcnt(4)
	v_mfma_f32_32x32x16_bf16 v[66:81], v[202:205], v[122:125], v[66:81]
	s_waitcnt lgkmcnt(3)
	v_mfma_f32_32x32x16_bf16 v[82:97], v[206:209], v[118:121], v[82:97]
	s_add_i32 s21, s31, s20
	s_mov_b32 m0, s21
	v_lshl_add_u64 v[226:227], v[182:183], 0, s[16:17]
	global_load_lds_dwordx4 v[226:227], off
	s_waitcnt lgkmcnt(2)
	v_mfma_f32_32x32x16_bf16 v[66:81], v[210:213], v[118:121], v[66:81]
	s_waitcnt lgkmcnt(1)
	v_mfma_f32_32x32x16_bf16 v[82:97], v[214:217], v[114:117], v[82:97]
	s_add_i32 s21, s34, s20
	s_mov_b32 m0, s21
	v_lshl_add_u64 v[226:227], v[180:181], 0, s[16:17]
	global_load_lds_dwordx4 v[226:227], off
	s_mov_b32 m0, s22
	s_waitcnt lgkmcnt(0)
	v_mfma_f32_32x32x16_bf16 v[66:81], v[218:221], v[114:117], v[66:81]
	v_add_u32_e32 v192, v0, v253
	ds_read_b128 v[188:191], v192
	ds_read_b128 v[202:205], v192 offset:8192
	v_add_u32_e32 v192, v0, v252
	ds_read_b128 v[206:209], v192
	ds_read_b128 v[210:213], v192 offset:8192
	v_add_u32_e32 v192, v0, v251
	v_add_u32_e32 v0, v0, v254
	ds_read_b128 v[214:217], v192
	ds_read_b128 v[218:221], v192 offset:8192
	ds_read_b128 v[222:225], v0
	ds_read_b128 v[192:195], v0 offset:8192
	s_waitcnt lgkmcnt(7)
	v_mfma_f32_32x32x16_bf16 v[82:97], v[188:191], v[110:113], v[82:97]
	s_waitcnt lgkmcnt(6)
	v_mfma_f32_32x32x16_bf16 v[66:81], v[202:205], v[110:113], v[66:81]
	s_waitcnt lgkmcnt(5)
	v_mfma_f32_32x32x16_bf16 v[82:97], v[206:209], v[106:109], v[82:97]
	s_waitcnt lgkmcnt(4)
	v_mfma_f32_32x32x16_bf16 v[66:81], v[210:213], v[106:109], v[66:81]
	s_waitcnt lgkmcnt(3)
	v_mfma_f32_32x32x16_bf16 v[82:97], v[214:217], v[102:105], v[82:97]
	s_waitcnt lgkmcnt(2)
	v_mfma_f32_32x32x16_bf16 v[66:81], v[218:221], v[102:105], v[66:81]
	s_waitcnt lgkmcnt(1)
	v_mfma_f32_32x32x16_bf16 v[82:97], v[222:225], v[98:101], v[82:97]
	s_waitcnt lgkmcnt(0)
	v_mfma_f32_32x32x16_bf16 v[66:81], v[192:195], v[98:101], v[66:81]
	s_cmp_eq_u32 s14, s19
	s_cbranch_scc0 .Lret_nondiag_m
	v_mov_b32_e32 v188, v132
	v_mov_b32_e32 v189, v133
	v_mov_b32_e32 v190, v134
	v_mov_b32_e32 v191, v135
	v_mov_b32_e32 v192, v136
	v_mov_b32_e32 v193, v137
	v_mov_b32_e32 v202, v138
	v_mov_b32_e32 v203, v139
	v_mov_b32_e32 v204, v140
	v_mov_b32_e32 v205, v141
	v_mov_b32_e32 v208, v142
	v_mov_b32_e32 v209, v143
	v_mov_b32_e32 v214, v146
	v_mov_b32_e32 v215, v147
	v_mov_b32_e32 v216, v148
	v_mov_b32_e32 v217, v149
	v_mov_b32_e32 v206, v144
	v_mov_b32_e32 v207, v145
	v_mov_b32_e32 v210, v150
	v_mov_b32_e32 v211, v151
	v_mov_b32_e32 v212, v152
	v_mov_b32_e32 v213, v153
	v_mov_b32_e32 v218, v154
	v_mov_b32_e32 v219, v155
	v_mov_b32_e32 v220, v156
	v_mov_b32_e32 v221, v157
	v_mov_b32_e32 v222, v158
	v_mov_b32_e32 v223, v159
	v_mov_b32_e32 v224, v160
	v_mov_b32_e32 v225, v161
	v_mov_b32_e32 v226, v162
	v_mov_b32_e32 v227, v163
	s_branch .LBB0_431
.Lret_nondiag_m:
	v_cvt_f32_i32_e32 v0, v198
	v_mul_f32_e32 v0, v230, v0
	v_exp_f32_e32 v206, v0
	s_nop 0
	v_mul_f32_e32 v188, v243, v206
	v_mul_f32_e32 v212, v244, v206
	v_mul_f32_e32 v192, v244, v188
	v_mul_f32_e32 v220, v244, v212
	v_mul_f32_e32 v204, v244, v192
	v_mul_f32_e32 v224, v244, v220
	v_mul_f32_e32 v214, v244, v204
	v_mul_f32_e32 v207, v242, v206
	v_mul_f32_e32 v213, v242, v212
	v_mul_f32_e32 v221, v242, v220
	v_mul_f32_e32 v225, v242, v224
	v_mul_f32_e32 v189, v242, v188
	v_mul_f32_e32 v193, v242, v192
	v_mul_f32_e32 v205, v242, v204
	v_mul_f32_e32 v215, v242, v214
	v_mul_f32_e32 v210, v242, v207
	v_mul_f32_e32 v218, v242, v213
	v_mul_f32_e32 v222, v242, v221
	v_mul_f32_e32 v226, v242, v225
	v_mul_f32_e32 v190, v242, v189
	v_mul_f32_e32 v202, v242, v193
	v_mul_f32_e32 v208, v242, v205
	v_mul_f32_e32 v216, v242, v215
	v_mul_f32_e32 v211, v242, v210
	v_mul_f32_e32 v219, v242, v218
	v_mul_f32_e32 v223, v242, v222
	v_mul_f32_e32 v227, v242, v226
	v_mul_f32_e32 v191, v242, v190
	v_mul_f32_e32 v203, v242, v202
	v_mul_f32_e32 v209, v242, v208
	v_mul_f32_e32 v217, v242, v216

.Lret_skip_dma:
	v_lshl_add_u64 v[66:67], v[186:187], 0, s[16:17]
	s_add_i32 s21, s29, s20
	s_mov_b32 s22, m0
	s_mov_b32 m0, s21
	s_nop 0
	global_load_lds_dwordx4 v[66:67], off
	s_mov_b32 m0, s22
	v_lshl_add_u64 v[66:67], v[184:185], 0, s[16:17]
	s_add_i32 s21, s30, s20
	s_mov_b32 s22, m0
	s_mov_b32 m0, s21
	s_nop 0
	global_load_lds_dwordx4 v[66:67], off
	s_mov_b32 m0, s22
	v_lshl_add_u64 v[66:67], v[182:183], 0, s[16:17]
	s_add_i32 s21, s31, s20
	s_mov_b32 s22, m0
	s_mov_b32 m0, s21
	s_nop 0
	global_load_lds_dwordx4 v[66:67], off
	s_mov_b32 m0, s22
	v_lshl_add_u64 v[66:67], v[180:181], 0, s[16:17]
	s_add_i32 s20, s34, s20
	s_mov_b32 s21, m0
	s_mov_b32 m0, s20
	s_nop 0
	global_load_lds_dwordx4 v[66:67], off
	s_mov_b32 m0, s21
	s_branch .LBB0_432
